# layer-1 in-projection GEMM: LDS ring rotated so k-step 0 lives in the buffer the epilogue never touches; next tile's origin, DMA pointers and k-step-0 LDS-DMA issued after the last k-step (lever 7.10)
# speedup vs baseline: 1.0271x; 1.0015x over previous
.LBB0_576:
.LBB0_577:
	v_readlane_b32 s0, v246, 20
	v_readlane_b32 s1, v246, 21
	s_andn2_b64 vcc, exec, s[0:1]
	s_cbranch_vccnz .LBB0_582
	v_readlane_b32 s2, v246, 46
	s_mov_b32 s101, 0
.LBB0_579:
	s_ashr_i32 s0, s2, 31
	s_lshr_b32 s1, s0, 26
	s_add_i32 s1, s2, s1
	s_ashr_i32 s22, s1, 6
	s_and_b32 s23, s1, 0xffc0
	s_lshr_b32 s1, s1, 31
	s_add_i32 s1, s22, s1
	s_sub_i32 s23, s2, s23
	s_and_b32 s1, s1, 0x1ffffe
	s_sub_i32 s1, s22, s1
	s_bfe_i32 s22, s23, 0x80000
	s_bfe_u32 s22, s22, 0x3000c
	s_lshr_b32 s0, s0, 25
	s_add_i32 s22, s23, s22
	s_add_i32 s0, s2, s0
	s_bfe_i32 s24, s22, 0x80000
	s_sext_i32_i16 s24, s24
	s_lshr_b32 s0, s0, 1
	s_and_b32 s0, s0, 0x1ffffc0
	s_and_b32 s24, s24, -8
	s_add_i32 s24, s24, s0
	v_readlane_b32 s0, v246, 0
	s_and_b32 s22, s22, 0xf8
	s_or_b32 s0, s24, s0
	s_sub_i32 s22, s23, s22
	s_sext_i32_i8 s23, s22
	s_lshl_b32 s22, s0, 7
	s_lshl_b32 s0, s1, 11
	s_lshl_b32 s23, s23, 8
	s_add_i32 s23, s23, s0
	s_barrier
	v_lshrrev_b32_e32 v226, 6, v184
	v_and_b32_e32 v227, 63, v184
	v_readfirstlane_b32 s6, v226
	v_lshrrev_b32_e32 v228, 2, v227
	v_bfe_u32 v229, v227, 4, 2
	v_and_b32_e32 v230, 3, v227
	v_xor_b32_e32 v229, v230, v229
	v_lshlrev_b32_e32 v229, 4, v229
	v_lshl_add_u32 v228, v228, 11, v229
	v_mov_b32_e32 v229, 0
	s_lshl_b32 s8, s6, 11
	s_lshl_b32 s9, s6, 12
	s_add_u32 s9, s9, 0x2000
	s_mov_b32 s10, 64
	s_mov_b32 s11, 0
	s_cmp_eq_u32 s101, 1
	s_cbranch_scc1 .Lgemm2_p7_skip
	v_readlane_b32 s4, v246, 4
	v_readlane_b32 s5, v246, 5
	v_readlane_b32 s12, v246, 18
	v_readlane_b32 s13, v246, 19
	s_nop 3
	s_lshl_b32 s0, s6, 5
	s_add_i32 s0, s0, s22
	s_lshl_b32 s0, s0, 11
	s_add_u32 s4, s4, s0
	s_addc_u32 s5, s5, 0
	v_lshl_add_u64 v[202:203], v[228:229], 0, s[4:5]
	s_add_u32 s4, s4, 0x8000
	s_addc_u32 s5, s5, 0
	v_lshl_add_u64 v[204:205], v[228:229], 0, s[4:5]
	s_lshl_b32 s0, s6, 6
	s_add_i32 s0, s0, s23
	s_lshl_b32 s0, s0, 11
	s_add_u32 s12, s12, s0
	s_addc_u32 s13, s13, 0
	v_lshl_add_u64 v[206:207], v[228:229], 0, s[12:13]
	s_add_u32 s12, s12, 0x8000
	s_addc_u32 s13, s13, 0
	v_lshl_add_u64 v[208:209], v[228:229], 0, s[12:13]
	s_add_u32 s12, s12, 0x8000
	s_addc_u32 s13, s13, 0
	v_lshl_add_u64 v[210:211], v[228:229], 0, s[12:13]
	s_add_u32 s12, s12, 0x8000
	s_addc_u32 s13, s13, 0
	v_lshl_add_u64 v[212:213], v[228:229], 0, s[12:13]
	s_add_u32 m0, s8, 0xc010
	s_nop 0
	global_load_lds_dwordx4 v[202:203], off
	v_lshl_add_u64 v[202:203], v[202:203], 0, s[10:11]
	s_add_u32 m0, s8, 0xc410
	s_nop 0
	global_load_lds_dwordx4 v[204:205], off
	v_lshl_add_u64 v[204:205], v[204:205], 0, s[10:11]
	s_add_u32 m0, s9, 0xc010
	s_nop 0
	global_load_lds_dwordx4 v[206:207], off
	v_lshl_add_u64 v[206:207], v[206:207], 0, s[10:11]
	s_add_u32 m0, s9, 0xc410
	s_nop 0
	global_load_lds_dwordx4 v[208:209], off
	v_lshl_add_u64 v[208:209], v[208:209], 0, s[10:11]
	s_add_u32 m0, s9, 0xc810
	s_nop 0
	global_load_lds_dwordx4 v[210:211], off
	v_lshl_add_u64 v[210:211], v[210:211], 0, s[10:11]
	s_add_u32 m0, s9, 0xcc10
	s_nop 0
	global_load_lds_dwordx4 v[212:213], off
	v_lshl_add_u64 v[212:213], v[212:213], 0, s[10:11]
.Lgemm2_p7_skip:
	s_add_u32 m0, s8, 0x0
	s_nop 0
	global_load_lds_dwordx4 v[202:203], off
	v_lshl_add_u64 v[202:203], v[202:203], 0, s[10:11]
	s_add_u32 m0, s8, 0x400
	s_nop 0
	global_load_lds_dwordx4 v[204:205], off
	v_lshl_add_u64 v[204:205], v[204:205], 0, s[10:11]
	s_add_u32 m0, s9, 0x0
	s_nop 0
	global_load_lds_dwordx4 v[206:207], off
	v_lshl_add_u64 v[206:207], v[206:207], 0, s[10:11]
	s_add_u32 m0, s9, 0x400
	s_nop 0
	global_load_lds_dwordx4 v[208:209], off
	v_lshl_add_u64 v[208:209], v[208:209], 0, s[10:11]
	s_add_u32 m0, s9, 0x800
	s_nop 0
	global_load_lds_dwordx4 v[210:211], off
	v_lshl_add_u64 v[210:211], v[210:211], 0, s[10:11]
	s_add_u32 m0, s9, 0xc00
	s_nop 0
	global_load_lds_dwordx4 v[212:213], off
	v_lshl_add_u64 v[212:213], v[212:213], 0, s[10:11]
	v_and_b32_e32 v230, 31, v227
	v_lshrrev_b32_e32 v238, 5, v227
	v_bfe_u32 v232, v230, 2, 2
	v_xor_b32_e32 v233, v238, v232
	v_xor_b32_e32 v234, 2, v233
	v_lshlrev_b32_e32 v233, 4, v233
	v_lshlrev_b32_e32 v234, 4, v234
	v_lshlrev_b32_e32 v235, 6, v230
	v_lshrrev_b32_e32 v236, 1, v226
	v_and_b32_e32 v237, 1, v226
	v_lshl_add_u32 v236, v236, 12, v235
	v_lshl_add_u32 v237, v237, 13, v235
	v_add_u32_e32 v237, 0x2000, v237
	v_add_u32_e32 v214, v233, v236
	v_add_u32_e32 v216, v233, v237
	v_add_u32_e32 v215, v234, v236
	v_add_u32_e32 v217, v234, v237
	v_add_u32_e32 v218, 0x6000, v214
	v_add_u32_e32 v220, 0x6000, v216
	v_add_u32_e32 v219, 0x6000, v215
	v_add_u32_e32 v221, 0x6000, v217
	v_add_u32_e32 v222, 0xc010, v214
	v_add_u32_e32 v224, 0xc010, v216
	v_add_u32_e32 v223, 0xc010, v215
	v_add_u32_e32 v225, 0xc010, v217
	v_mov_b32_e32 v2, 0
	v_mov_b32_e32 v3, v2
	v_mov_b32_e32 v4, v2
	v_mov_b32_e32 v5, v2
	v_mov_b32_e32 v6, v2
	v_mov_b32_e32 v7, v2
	v_mov_b32_e32 v8, v2
	v_mov_b32_e32 v9, v2
	v_mov_b32_e32 v10, v2
	v_mov_b32_e32 v11, v2
	v_mov_b32_e32 v12, v2
	v_mov_b32_e32 v13, v2
	v_mov_b32_e32 v14, v2
	v_mov_b32_e32 v15, v2
	v_mov_b32_e32 v16, v2
	v_mov_b32_e32 v17, v2
	v_mov_b32_e32 v18, v2
	v_mov_b32_e32 v19, v2
	v_mov_b32_e32 v20, v2
	v_mov_b32_e32 v21, v2
	v_mov_b32_e32 v22, v2
	v_mov_b32_e32 v23, v2
	v_mov_b32_e32 v24, v2
	v_mov_b32_e32 v25, v2
	v_mov_b32_e32 v26, v2
	v_mov_b32_e32 v27, v2
	v_mov_b32_e32 v28, v2
	v_mov_b32_e32 v29, v2
	v_mov_b32_e32 v30, v2
	v_mov_b32_e32 v31, v2
	v_mov_b32_e32 v32, v2
	v_mov_b32_e32 v33, v2
	v_mov_b32_e32 v34, v2
	v_mov_b32_e32 v35, v2
	v_mov_b32_e32 v36, v2
	v_mov_b32_e32 v37, v2
	v_mov_b32_e32 v38, v2
	v_mov_b32_e32 v39, v2
	v_mov_b32_e32 v40, v2
	v_mov_b32_e32 v41, v2
	v_mov_b32_e32 v42, v2
	v_mov_b32_e32 v43, v2
	v_mov_b32_e32 v44, v2
	v_mov_b32_e32 v45, v2
	v_mov_b32_e32 v46, v2
	v_mov_b32_e32 v47, v2
	v_mov_b32_e32 v48, v2
	v_mov_b32_e32 v49, v2
	v_mov_b32_e32 v50, v2
	v_mov_b32_e32 v51, v2
	v_mov_b32_e32 v52, v2
	v_mov_b32_e32 v53, v2
	v_mov_b32_e32 v54, v2
	v_mov_b32_e32 v55, v2
	v_mov_b32_e32 v56, v2
	v_mov_b32_e32 v57, v2
	v_mov_b32_e32 v58, v2
	v_mov_b32_e32 v59, v2
	v_mov_b32_e32 v60, v2
	v_mov_b32_e32 v61, v2
	v_mov_b32_e32 v62, v2
	v_mov_b32_e32 v63, v2
	v_mov_b32_e32 v64, v2
	v_mov_b32_e32 v65, v2
	v_mov_b32_e32 v66, v2
	v_mov_b32_e32 v67, v2
	v_mov_b32_e32 v68, v2
	v_mov_b32_e32 v69, v2
	v_mov_b32_e32 v70, v2
	v_mov_b32_e32 v71, v2
	v_mov_b32_e32 v72, v2
	v_mov_b32_e32 v73, v2
	v_mov_b32_e32 v74, v2
	v_mov_b32_e32 v75, v2
	v_mov_b32_e32 v76, v2
	v_mov_b32_e32 v77, v2
	v_mov_b32_e32 v78, v2
	v_mov_b32_e32 v79, v2
	v_mov_b32_e32 v80, v2
	v_mov_b32_e32 v81, v2
	v_mov_b32_e32 v82, v2
	v_mov_b32_e32 v83, v2
	v_mov_b32_e32 v84, v2
	v_mov_b32_e32 v85, v2
	v_mov_b32_e32 v86, v2
	v_mov_b32_e32 v87, v2
	v_mov_b32_e32 v88, v2
	v_mov_b32_e32 v89, v2
	v_mov_b32_e32 v90, v2
	v_mov_b32_e32 v91, v2
	v_mov_b32_e32 v92, v2
	v_mov_b32_e32 v93, v2
	v_mov_b32_e32 v94, v2
	v_mov_b32_e32 v95, v2
	v_mov_b32_e32 v96, v2
	v_mov_b32_e32 v97, v2
	v_mov_b32_e32 v98, v2
	v_mov_b32_e32 v99, v2
	v_mov_b32_e32 v100, v2
	v_mov_b32_e32 v101, v2
	v_mov_b32_e32 v102, v2
	v_mov_b32_e32 v103, v2
	v_mov_b32_e32 v104, v2
	v_mov_b32_e32 v105, v2
	v_mov_b32_e32 v106, v2
	v_mov_b32_e32 v107, v2
	v_mov_b32_e32 v108, v2
	v_mov_b32_e32 v109, v2
	v_mov_b32_e32 v110, v2
	v_mov_b32_e32 v111, v2
	v_mov_b32_e32 v112, v2
	v_mov_b32_e32 v113, v2
	v_mov_b32_e32 v114, v2
	v_mov_b32_e32 v115, v2
	v_mov_b32_e32 v116, v2
	v_mov_b32_e32 v117, v2
	v_mov_b32_e32 v118, v2
	v_mov_b32_e32 v119, v2
	v_mov_b32_e32 v120, v2
	v_mov_b32_e32 v121, v2
	v_mov_b32_e32 v122, v2
	v_mov_b32_e32 v123, v2
	v_mov_b32_e32 v124, v2
	v_mov_b32_e32 v125, v2
	v_mov_b32_e32 v126, v2
	v_mov_b32_e32 v127, v2
	v_mov_b32_e32 v128, v2
	v_mov_b32_e32 v129, v2
	s_mov_b32 s7, 10
.Lgemm2_p7_loop:
	s_waitcnt vmcnt(6)
	s_barrier
	ds_read_b128 v[130:133], v222
	ds_read_b128 v[134:137], v222 offset:2048
	ds_read_b128 v[138:141], v224
	ds_read_b128 v[142:145], v224 offset:2048
	ds_read_b128 v[146:149], v224 offset:4096
	ds_read_b128 v[150:153], v224 offset:6144
	ds_read_b128 v[154:157], v223
	ds_read_b128 v[158:161], v223 offset:2048
	ds_read_b128 v[162:165], v225
	ds_read_b128 v[166:169], v225 offset:2048
	ds_read_b128 v[170:173], v225 offset:4096
	ds_read_b128 v[174:177], v225 offset:6144
	s_add_u32 m0, s8, 0x6000
	s_nop 0
	global_load_lds_dwordx4 v[202:203], off
	v_lshl_add_u64 v[202:203], v[202:203], 0, s[10:11]
	s_waitcnt lgkmcnt(9)
	v_mfma_f32_32x32x16_bf16 v[114:129], v[138:141], v[130:133], v[114:129]
	v_mfma_f32_32x32x16_bf16 v[98:113], v[138:141], v[134:137], v[98:113]
	s_add_u32 m0, s8, 0x6400
	s_nop 0
	global_load_lds_dwordx4 v[204:205], off
	v_lshl_add_u64 v[204:205], v[204:205], 0, s[10:11]
	s_waitcnt lgkmcnt(8)
	v_mfma_f32_32x32x16_bf16 v[82:97], v[142:145], v[130:133], v[82:97]
	v_mfma_f32_32x32x16_bf16 v[66:81], v[142:145], v[134:137], v[66:81]
	s_add_u32 m0, s9, 0x6000
	s_nop 0
	global_load_lds_dwordx4 v[206:207], off
	v_lshl_add_u64 v[206:207], v[206:207], 0, s[10:11]
	s_waitcnt lgkmcnt(7)
	v_mfma_f32_32x32x16_bf16 v[50:65], v[146:149], v[130:133], v[50:65]
	v_mfma_f32_32x32x16_bf16 v[34:49], v[146:149], v[134:137], v[34:49]
	s_add_u32 m0, s9, 0x6400
	s_nop 0
	global_load_lds_dwordx4 v[208:209], off
	v_lshl_add_u64 v[208:209], v[208:209], 0, s[10:11]
	s_waitcnt lgkmcnt(6)
	v_mfma_f32_32x32x16_bf16 v[18:33], v[150:153], v[130:133], v[18:33]
	v_mfma_f32_32x32x16_bf16 v[2:17], v[150:153], v[134:137], v[2:17]
	s_add_u32 m0, s9, 0x6800
	s_nop 0
	global_load_lds_dwordx4 v[210:211], off
	v_lshl_add_u64 v[210:211], v[210:211], 0, s[10:11]
	s_waitcnt lgkmcnt(3)
	v_mfma_f32_32x32x16_bf16 v[114:129], v[162:165], v[154:157], v[114:129]
	v_mfma_f32_32x32x16_bf16 v[98:113], v[162:165], v[158:161], v[98:113]
	s_add_u32 m0, s9, 0x6c00
	s_nop 0
	global_load_lds_dwordx4 v[212:213], off
	v_lshl_add_u64 v[212:213], v[212:213], 0, s[10:11]
	s_waitcnt lgkmcnt(2)
	v_mfma_f32_32x32x16_bf16 v[82:97], v[166:169], v[154:157], v[82:97]
	v_mfma_f32_32x32x16_bf16 v[66:81], v[166:169], v[158:161], v[66:81]
	s_waitcnt lgkmcnt(1)
	v_mfma_f32_32x32x16_bf16 v[50:65], v[170:173], v[154:157], v[50:65]
	v_mfma_f32_32x32x16_bf16 v[34:49], v[170:173], v[158:161], v[34:49]
	s_waitcnt lgkmcnt(0)
	v_mfma_f32_32x32x16_bf16 v[18:33], v[174:177], v[154:157], v[18:33]
	v_mfma_f32_32x32x16_bf16 v[2:17], v[174:177], v[158:161], v[2:17]
	s_waitcnt vmcnt(6)
	s_barrier
	ds_read_b128 v[130:133], v214
	ds_read_b128 v[134:137], v214 offset:2048
	ds_read_b128 v[138:141], v216
	ds_read_b128 v[142:145], v216 offset:2048
	ds_read_b128 v[146:149], v216 offset:4096
	ds_read_b128 v[150:153], v216 offset:6144
	ds_read_b128 v[154:157], v215
	ds_read_b128 v[158:161], v215 offset:2048
	ds_read_b128 v[162:165], v217
	ds_read_b128 v[166:169], v217 offset:2048
	ds_read_b128 v[170:173], v217 offset:4096
	ds_read_b128 v[174:177], v217 offset:6144
	s_add_u32 m0, s8, 0xc010
	s_nop 0
	global_load_lds_dwordx4 v[202:203], off
	v_lshl_add_u64 v[202:203], v[202:203], 0, s[10:11]
	s_waitcnt lgkmcnt(9)
	v_mfma_f32_32x32x16_bf16 v[114:129], v[138:141], v[130:133], v[114:129]
	v_mfma_f32_32x32x16_bf16 v[98:113], v[138:141], v[134:137], v[98:113]
	s_add_u32 m0, s8, 0xc410
	s_nop 0
	global_load_lds_dwordx4 v[204:205], off
	v_lshl_add_u64 v[204:205], v[204:205], 0, s[10:11]
	s_waitcnt lgkmcnt(8)
	v_mfma_f32_32x32x16_bf16 v[82:97], v[142:145], v[130:133], v[82:97]
	v_mfma_f32_32x32x16_bf16 v[66:81], v[142:145], v[134:137], v[66:81]
	s_add_u32 m0, s9, 0xc010
	s_nop 0
	global_load_lds_dwordx4 v[206:207], off
	v_lshl_add_u64 v[206:207], v[206:207], 0, s[10:11]
	s_waitcnt lgkmcnt(7)
	v_mfma_f32_32x32x16_bf16 v[50:65], v[146:149], v[130:133], v[50:65]
	v_mfma_f32_32x32x16_bf16 v[34:49], v[146:149], v[134:137], v[34:49]
	s_add_u32 m0, s9, 0xc410
	s_nop 0
	global_load_lds_dwordx4 v[208:209], off
	v_lshl_add_u64 v[208:209], v[208:209], 0, s[10:11]
	s_waitcnt lgkmcnt(6)
	v_mfma_f32_32x32x16_bf16 v[18:33], v[150:153], v[130:133], v[18:33]
	v_mfma_f32_32x32x16_bf16 v[2:17], v[150:153], v[134:137], v[2:17]
	s_add_u32 m0, s9, 0xc810
	s_nop 0
	global_load_lds_dwordx4 v[210:211], off
	v_lshl_add_u64 v[210:211], v[210:211], 0, s[10:11]
	s_waitcnt lgkmcnt(3)
	v_mfma_f32_32x32x16_bf16 v[114:129], v[162:165], v[154:157], v[114:129]
	v_mfma_f32_32x32x16_bf16 v[98:113], v[162:165], v[158:161], v[98:113]
	s_add_u32 m0, s9, 0xcc10
	s_nop 0
	global_load_lds_dwordx4 v[212:213], off
	v_lshl_add_u64 v[212:213], v[212:213], 0, s[10:11]
	s_waitcnt lgkmcnt(2)
	v_mfma_f32_32x32x16_bf16 v[82:97], v[166:169], v[154:157], v[82:97]
	v_mfma_f32_32x32x16_bf16 v[66:81], v[166:169], v[158:161], v[66:81]
	s_waitcnt lgkmcnt(1)
	v_mfma_f32_32x32x16_bf16 v[50:65], v[170:173], v[154:157], v[50:65]
	v_mfma_f32_32x32x16_bf16 v[34:49], v[170:173], v[158:161], v[34:49]
	s_waitcnt lgkmcnt(0)
	v_mfma_f32_32x32x16_bf16 v[18:33], v[174:177], v[154:157], v[18:33]
	v_mfma_f32_32x32x16_bf16 v[2:17], v[174:177], v[158:161], v[2:17]
	s_waitcnt vmcnt(6)
	s_barrier
	ds_read_b128 v[130:133], v218
	ds_read_b128 v[134:137], v218 offset:2048
	ds_read_b128 v[138:141], v220
	ds_read_b128 v[142:145], v220 offset:2048
	ds_read_b128 v[146:149], v220 offset:4096
	ds_read_b128 v[150:153], v220 offset:6144
	ds_read_b128 v[154:157], v219
	ds_read_b128 v[158:161], v219 offset:2048
	ds_read_b128 v[162:165], v221
	ds_read_b128 v[166:169], v221 offset:2048
	ds_read_b128 v[170:173], v221 offset:4096
	ds_read_b128 v[174:177], v221 offset:6144
	s_add_u32 m0, s8, 0x0
	s_nop 0
	global_load_lds_dwordx4 v[202:203], off
	v_lshl_add_u64 v[202:203], v[202:203], 0, s[10:11]
	s_waitcnt lgkmcnt(9)
	v_mfma_f32_32x32x16_bf16 v[114:129], v[138:141], v[130:133], v[114:129]
	v_mfma_f32_32x32x16_bf16 v[98:113], v[138:141], v[134:137], v[98:113]
	s_add_u32 m0, s8, 0x400
	s_nop 0
	global_load_lds_dwordx4 v[204:205], off
	v_lshl_add_u64 v[204:205], v[204:205], 0, s[10:11]
	s_waitcnt lgkmcnt(8)
	v_mfma_f32_32x32x16_bf16 v[82:97], v[142:145], v[130:133], v[82:97]
	v_mfma_f32_32x32x16_bf16 v[66:81], v[142:145], v[134:137], v[66:81]
	s_add_u32 m0, s9, 0x0
	s_nop 0
	global_load_lds_dwordx4 v[206:207], off
	v_lshl_add_u64 v[206:207], v[206:207], 0, s[10:11]
	s_waitcnt lgkmcnt(7)
	v_mfma_f32_32x32x16_bf16 v[50:65], v[146:149], v[130:133], v[50:65]
	v_mfma_f32_32x32x16_bf16 v[34:49], v[146:149], v[134:137], v[34:49]
	s_add_u32 m0, s9, 0x400
	s_nop 0
	global_load_lds_dwordx4 v[208:209], off
	v_lshl_add_u64 v[208:209], v[208:209], 0, s[10:11]
	s_waitcnt lgkmcnt(6)
	v_mfma_f32_32x32x16_bf16 v[18:33], v[150:153], v[130:133], v[18:33]
	v_mfma_f32_32x32x16_bf16 v[2:17], v[150:153], v[134:137], v[2:17]
	s_add_u32 m0, s9, 0x800
	s_nop 0
	global_load_lds_dwordx4 v[210:211], off
	v_lshl_add_u64 v[210:211], v[210:211], 0, s[10:11]
	s_waitcnt lgkmcnt(3)
	v_mfma_f32_32x32x16_bf16 v[114:129], v[162:165], v[154:157], v[114:129]
	v_mfma_f32_32x32x16_bf16 v[98:113], v[162:165], v[158:161], v[98:113]
	s_add_u32 m0, s9, 0xc00
	s_nop 0
	global_load_lds_dwordx4 v[212:213], off
	v_lshl_add_u64 v[212:213], v[212:213], 0, s[10:11]
	s_waitcnt lgkmcnt(2)
	v_mfma_f32_32x32x16_bf16 v[82:97], v[166:169], v[154:157], v[82:97]
	v_mfma_f32_32x32x16_bf16 v[66:81], v[166:169], v[158:161], v[66:81]
	s_waitcnt lgkmcnt(1)
	v_mfma_f32_32x32x16_bf16 v[50:65], v[170:173], v[154:157], v[50:65]
	v_mfma_f32_32x32x16_bf16 v[34:49], v[170:173], v[158:161], v[34:49]
	s_waitcnt lgkmcnt(0)
	v_mfma_f32_32x32x16_bf16 v[18:33], v[174:177], v[154:157], v[18:33]
	v_mfma_f32_32x32x16_bf16 v[2:17], v[174:177], v[158:161], v[2:17]
	s_sub_u32 s7, s7, 1
	s_cmp_lg_u32 s7, 0
	s_cbranch_scc1 .Lgemm2_p7_loop
	s_waitcnt vmcnt(6)
	s_barrier
	ds_read_b128 v[130:133], v222
	ds_read_b128 v[134:137], v222 offset:2048
	ds_read_b128 v[138:141], v224
	ds_read_b128 v[142:145], v224 offset:2048
	ds_read_b128 v[146:149], v224 offset:4096
	ds_read_b128 v[150:153], v224 offset:6144
	ds_read_b128 v[154:157], v223
	ds_read_b128 v[158:161], v223 offset:2048
	ds_read_b128 v[162:165], v225
	ds_read_b128 v[166:169], v225 offset:2048
	ds_read_b128 v[170:173], v225 offset:4096
	ds_read_b128 v[174:177], v225 offset:6144
	s_waitcnt lgkmcnt(9)
	v_mfma_f32_32x32x16_bf16 v[114:129], v[138:141], v[130:133], v[114:129]
	v_mfma_f32_32x32x16_bf16 v[98:113], v[138:141], v[134:137], v[98:113]
	s_waitcnt lgkmcnt(8)
	v_mfma_f32_32x32x16_bf16 v[82:97], v[142:145], v[130:133], v[82:97]
	v_mfma_f32_32x32x16_bf16 v[66:81], v[142:145], v[134:137], v[66:81]
	s_waitcnt lgkmcnt(7)
	v_mfma_f32_32x32x16_bf16 v[50:65], v[146:149], v[130:133], v[50:65]
	v_mfma_f32_32x32x16_bf16 v[34:49], v[146:149], v[134:137], v[34:49]
	s_waitcnt lgkmcnt(6)
	v_mfma_f32_32x32x16_bf16 v[18:33], v[150:153], v[130:133], v[18:33]
	v_mfma_f32_32x32x16_bf16 v[2:17], v[150:153], v[134:137], v[2:17]
	s_waitcnt lgkmcnt(3)
	v_mfma_f32_32x32x16_bf16 v[114:129], v[162:165], v[154:157], v[114:129]
	v_mfma_f32_32x32x16_bf16 v[98:113], v[162:165], v[158:161], v[98:113]
	s_waitcnt lgkmcnt(2)
	v_mfma_f32_32x32x16_bf16 v[82:97], v[166:169], v[154:157], v[82:97]
	v_mfma_f32_32x32x16_bf16 v[66:81], v[166:169], v[158:161], v[66:81]
	s_waitcnt lgkmcnt(1)
	v_mfma_f32_32x32x16_bf16 v[50:65], v[170:173], v[154:157], v[50:65]
	v_mfma_f32_32x32x16_bf16 v[34:49], v[170:173], v[158:161], v[34:49]
	s_waitcnt lgkmcnt(0)
	v_mfma_f32_32x32x16_bf16 v[18:33], v[174:177], v[154:157], v[18:33]
	v_mfma_f32_32x32x16_bf16 v[2:17], v[174:177], v[158:161], v[2:17]
	s_waitcnt vmcnt(0)
	s_barrier
	ds_read_b128 v[130:133], v214
	ds_read_b128 v[134:137], v214 offset:2048
	ds_read_b128 v[138:141], v216
	ds_read_b128 v[142:145], v216 offset:2048
	ds_read_b128 v[146:149], v216 offset:4096
	ds_read_b128 v[150:153], v216 offset:6144
	ds_read_b128 v[154:157], v215
	ds_read_b128 v[158:161], v215 offset:2048
	ds_read_b128 v[162:165], v217
	ds_read_b128 v[166:169], v217 offset:2048
	ds_read_b128 v[170:173], v217 offset:4096
	ds_read_b128 v[174:177], v217 offset:6144
	s_waitcnt lgkmcnt(9)
	v_mfma_f32_32x32x16_bf16 v[114:129], v[138:141], v[130:133], v[114:129]
	v_mfma_f32_32x32x16_bf16 v[98:113], v[138:141], v[134:137], v[98:113]
	s_waitcnt lgkmcnt(8)
	v_mfma_f32_32x32x16_bf16 v[82:97], v[142:145], v[130:133], v[82:97]
	v_mfma_f32_32x32x16_bf16 v[66:81], v[142:145], v[134:137], v[66:81]
	s_waitcnt lgkmcnt(7)
	v_mfma_f32_32x32x16_bf16 v[50:65], v[146:149], v[130:133], v[50:65]
	v_mfma_f32_32x32x16_bf16 v[34:49], v[146:149], v[134:137], v[34:49]
	s_waitcnt lgkmcnt(6)
	v_mfma_f32_32x32x16_bf16 v[18:33], v[150:153], v[130:133], v[18:33]
	v_mfma_f32_32x32x16_bf16 v[2:17], v[150:153], v[134:137], v[2:17]
	s_waitcnt lgkmcnt(3)
	v_mfma_f32_32x32x16_bf16 v[114:129], v[162:165], v[154:157], v[114:129]
	v_mfma_f32_32x32x16_bf16 v[98:113], v[162:165], v[158:161], v[98:113]
	s_waitcnt lgkmcnt(2)
	v_mfma_f32_32x32x16_bf16 v[82:97], v[166:169], v[154:157], v[82:97]
	v_mfma_f32_32x32x16_bf16 v[66:81], v[166:169], v[158:161], v[66:81]
	s_waitcnt lgkmcnt(1)
	v_mfma_f32_32x32x16_bf16 v[50:65], v[170:173], v[154:157], v[50:65]
	v_mfma_f32_32x32x16_bf16 v[34:49], v[170:173], v[158:161], v[34:49]
	s_waitcnt lgkmcnt(0)
	v_mfma_f32_32x32x16_bf16 v[18:33], v[174:177], v[154:157], v[18:33]
	v_mfma_f32_32x32x16_bf16 v[2:17], v[174:177], v[158:161], v[2:17]
	v_readlane_b32 s13, v246, 1
	s_nop 1
	s_add_i32 s13, s2, s13
	s_mov_b32 s101, 0
	s_cmpk_gt_i32 s13, 0x27f
	s_cbranch_scc1 .Lgemm2_p7_nopf
	s_ashr_i32 s0, s13, 31
	s_lshr_b32 s1, s0, 26
	s_add_i32 s1, s13, s1
	s_ashr_i32 s7, s1, 6
	s_and_b32 s100, s1, 0xffc0
	s_lshr_b32 s1, s1, 31
	s_add_i32 s1, s7, s1
	s_sub_i32 s100, s13, s100
	s_and_b32 s1, s1, 0x1ffffe
	s_sub_i32 s1, s7, s1
	s_bfe_i32 s7, s100, 0x80000
	s_bfe_u32 s7, s7, 0x3000c
	s_lshr_b32 s0, s0, 25
	s_add_i32 s7, s100, s7
	s_add_i32 s0, s13, s0
	s_bfe_i32 s12, s7, 0x80000
	s_sext_i32_i16 s12, s12
	s_lshr_b32 s0, s0, 1
	s_and_b32 s0, s0, 0x1ffffc0
	s_and_b32 s12, s12, -8
	s_add_i32 s12, s12, s0
	v_readlane_b32 s0, v246, 0
	s_and_b32 s7, s7, 0xf8
	s_or_b32 s0, s12, s0
	s_sub_i32 s7, s100, s7
	s_sext_i32_i8 s100, s7
	s_lshl_b32 s7, s0, 7
	s_lshl_b32 s0, s1, 11
	s_lshl_b32 s100, s100, 8
	s_add_i32 s100, s100, s0
	v_lshrrev_b32_e32 v226, 6, v184
	v_and_b32_e32 v227, 63, v184
	v_readfirstlane_b32 s6, v226
	v_lshrrev_b32_e32 v228, 2, v227
	v_bfe_u32 v229, v227, 4, 2
	v_and_b32_e32 v230, 3, v227
	v_xor_b32_e32 v229, v230, v229
	v_lshlrev_b32_e32 v229, 4, v229
	v_lshl_add_u32 v228, v228, 11, v229
	v_mov_b32_e32 v229, 0
	v_readlane_b32 s4, v246, 4
	v_readlane_b32 s5, v246, 5
	v_readlane_b32 s12, v246, 18
	v_readlane_b32 s13, v246, 19
	s_nop 3
	s_lshl_b32 s0, s6, 5
	s_add_i32 s0, s0, s7
	s_lshl_b32 s0, s0, 11
	s_add_u32 s4, s4, s0
	s_addc_u32 s5, s5, 0
	v_lshl_add_u64 v[202:203], v[228:229], 0, s[4:5]
	s_add_u32 s4, s4, 0x8000
	s_addc_u32 s5, s5, 0
	v_lshl_add_u64 v[204:205], v[228:229], 0, s[4:5]
	s_lshl_b32 s0, s6, 6
	s_add_i32 s0, s0, s100
	s_lshl_b32 s0, s0, 11
	s_add_u32 s12, s12, s0
	s_addc_u32 s13, s13, 0
	v_lshl_add_u64 v[206:207], v[228:229], 0, s[12:13]
	s_add_u32 s12, s12, 0x8000
	s_addc_u32 s13, s13, 0
	v_lshl_add_u64 v[208:209], v[228:229], 0, s[12:13]
	s_add_u32 s12, s12, 0x8000
	s_addc_u32 s13, s13, 0
	v_lshl_add_u64 v[210:211], v[228:229], 0, s[12:13]
	s_add_u32 s12, s12, 0x8000
	s_addc_u32 s13, s13, 0
	v_lshl_add_u64 v[212:213], v[228:229], 0, s[12:13]
	s_add_u32 m0, s8, 0xc010
	s_nop 0
	global_load_lds_dwordx4 v[202:203], off
	v_lshl_add_u64 v[202:203], v[202:203], 0, s[10:11]
	s_add_u32 m0, s8, 0xc410
	s_nop 0
	global_load_lds_dwordx4 v[204:205], off
	v_lshl_add_u64 v[204:205], v[204:205], 0, s[10:11]
	s_add_u32 m0, s9, 0xc010
	s_nop 0
	global_load_lds_dwordx4 v[206:207], off
	v_lshl_add_u64 v[206:207], v[206:207], 0, s[10:11]
	s_add_u32 m0, s9, 0xc410
	s_nop 0
	global_load_lds_dwordx4 v[208:209], off
	v_lshl_add_u64 v[208:209], v[208:209], 0, s[10:11]
	s_add_u32 m0, s9, 0xc810
	s_nop 0
	global_load_lds_dwordx4 v[210:211], off
	v_lshl_add_u64 v[210:211], v[210:211], 0, s[10:11]
	s_add_u32 m0, s9, 0xcc10
	s_nop 0
	global_load_lds_dwordx4 v[212:213], off
	v_lshl_add_u64 v[212:213], v[212:213], 0, s[10:11]
	s_mov_b32 s101, 1
.Lgemm2_p7_nopf:
	s_movk_i32 s0, 0x2400
	v_mov_b32_e32 v131, v184
	s_nop 0
	v_ashrrev_i32_e32 v130, 1, v131
	v_ashrrev_i32_e32 v132, 6, v131
	v_and_b32_e32 v130, 0xffffffc0, v130
	v_lshlrev_b32_e32 v1, 7, v132
	v_add_u32_e32 v130, s22, v130
	v_mul_lo_u32 v133, v132, s0
	v_bfe_u32 v132, v131, 3, 3
	v_readlane_b32 s0, v247, 56
	v_readlane_b32 s1, v247, 57
	s_barrier
	v_and_b32_e32 v1, 0x80, v1
	v_or_b32_e32 v1, s23, v1
	v_lshrrev_b32_e32 v134, 3, v131
	v_and_b32_e32 v136, 4, v134
	v_lshlrev_b32_e32 v134, 1, v131
	v_lshlrev_b32_e32 v131, 4, v131
	v_and_or_b32 v137, v134, 62, v133
	v_and_b32_e32 v134, 0x70, v131
	v_ashrrev_i32_e32 v131, 31, v130
	v_lshl_add_u64 v[130:131], v[130:131], 1, s[0:1]
	v_mov_b32_e32 v135, v0
	s_movk_i32 s0, 0x90
	v_lshl_add_u64 v[130:131], v[130:131], 0, v[134:135]
	v_cvt_pk_bf16_f32 v114, v114, s0
	v_mad_u32_u24 v135, v136, s0, v137
	ds_write_b16 v135, v114
	v_cvt_pk_bf16_f32 v114, v115, s0
	ds_write_b16 v135, v114 offset:144
	v_cvt_pk_bf16_f32 v114, v116, s0
	v_or_b32_e32 v115, 3, v132
	ds_write_b16 v135, v114 offset:288
	v_cvt_pk_bf16_f32 v114, v117, s0
	v_mad_u32_u24 v115, v115, s0, v137
	ds_write_b16 v115, v114
	v_cvt_pk_bf16_f32 v114, v118, s0
	ds_write_b16 v135, v114 offset:1152
	v_cvt_pk_bf16_f32 v114, v119, s0
	ds_write_b16 v135, v114 offset:1296
	v_cvt_pk_bf16_f32 v114, v120, s0
	v_or_b32_e32 v116, 11, v132
	ds_write_b16 v135, v114 offset:1440
	v_cvt_pk_bf16_f32 v114, v121, s0
	v_mad_u32_u24 v116, v116, s0, v137
	ds_write_b16 v116, v114
	v_cvt_pk_bf16_f32 v114, v122, s0
	ds_write_b16 v135, v114 offset:2304
	v_cvt_pk_bf16_f32 v114, v123, s0
	ds_write_b16 v135, v114 offset:2448
	v_cvt_pk_bf16_f32 v114, v124, s0
	v_or_b32_e32 v117, 19, v132
	ds_write_b16 v135, v114 offset:2592
	v_cvt_pk_bf16_f32 v114, v125, s0
	v_mad_u32_u24 v117, v117, s0, v137
	ds_write_b16 v117, v114
	v_cvt_pk_bf16_f32 v114, v126, s0
	ds_write_b16 v135, v114 offset:3456
	v_cvt_pk_bf16_f32 v114, v127, s0
	ds_write_b16 v135, v114 offset:3600
	v_cvt_pk_bf16_f32 v114, v128, s0
	v_or_b32_e32 v118, 27, v132
	ds_write_b16 v135, v114 offset:3744
	v_cvt_pk_bf16_f32 v114, v129, s0
	v_mad_u32_u24 v118, v118, s0, v137
	v_cvt_pk_bf16_f32 v98, v98, s0
	ds_write_b16 v118, v114
	ds_write_b16 v135, v98 offset:64
	v_cvt_pk_bf16_f32 v98, v99, s0
	ds_write_b16 v135, v98 offset:208
	v_cvt_pk_bf16_f32 v98, v100, s0
	ds_write_b16 v135, v98 offset:352
	v_cvt_pk_bf16_f32 v98, v101, s0
	ds_write_b16 v115, v98 offset:64
	v_cvt_pk_bf16_f32 v98, v102, s0
	ds_write_b16 v135, v98 offset:1216
	v_cvt_pk_bf16_f32 v98, v103, s0
	ds_write_b16 v135, v98 offset:1360
	v_cvt_pk_bf16_f32 v98, v104, s0
	ds_write_b16 v135, v98 offset:1504
	v_cvt_pk_bf16_f32 v98, v105, s0
	ds_write_b16 v116, v98 offset:64
	v_cvt_pk_bf16_f32 v98, v106, s0
	ds_write_b16 v135, v98 offset:2368
	v_cvt_pk_bf16_f32 v98, v107, s0
	ds_write_b16 v135, v98 offset:2512
	v_cvt_pk_bf16_f32 v98, v108, s0
	ds_write_b16 v135, v98 offset:2656
	v_cvt_pk_bf16_f32 v98, v109, s0
	ds_write_b16 v117, v98 offset:64
	v_cvt_pk_bf16_f32 v98, v110, s0
	ds_write_b16 v135, v98 offset:3520
	v_cvt_pk_bf16_f32 v98, v111, s0
	ds_write_b16 v135, v98 offset:3664
	v_cvt_pk_bf16_f32 v98, v112, s0
	ds_write_b16 v135, v98 offset:3808
	v_cvt_pk_bf16_f32 v98, v113, s0
	v_cvt_pk_bf16_f32 v82, v82, s0
	ds_write_b16 v118, v98 offset:64
	ds_write_b16 v135, v82 offset:4608
	v_cvt_pk_bf16_f32 v82, v83, s0
	ds_write_b16 v135, v82 offset:4752
	v_cvt_pk_bf16_f32 v82, v84, s0
	v_or_b32_e32 v83, 35, v132
	ds_write_b16 v135, v82 offset:4896
	v_cvt_pk_bf16_f32 v82, v85, s0
	v_mad_u32_u24 v83, v83, s0, v137
	ds_write_b16 v83, v82
	v_cvt_pk_bf16_f32 v82, v86, s0
	ds_write_b16 v135, v82 offset:5760
	v_cvt_pk_bf16_f32 v82, v87, s0
	ds_write_b16 v135, v82 offset:5904
	v_cvt_pk_bf16_f32 v82, v88, s0
	v_or_b32_e32 v84, 43, v132
	ds_write_b16 v135, v82 offset:6048
	v_cvt_pk_bf16_f32 v82, v89, s0
	v_mad_u32_u24 v84, v84, s0, v137
	ds_write_b16 v84, v82
	v_cvt_pk_bf16_f32 v82, v90, s0
	ds_write_b16 v135, v82 offset:6912
	v_cvt_pk_bf16_f32 v82, v91, s0
	ds_write_b16 v135, v82 offset:7056
	v_cvt_pk_bf16_f32 v82, v92, s0
	v_or_b32_e32 v85, 51, v132
	ds_write_b16 v135, v82 offset:7200
	v_cvt_pk_bf16_f32 v82, v93, s0
	v_mad_u32_u24 v85, v85, s0, v137
	ds_write_b16 v85, v82
	v_cvt_pk_bf16_f32 v82, v94, s0
	ds_write_b16 v135, v82 offset:8064
	v_cvt_pk_bf16_f32 v82, v95, s0
	ds_write_b16 v135, v82 offset:8208
	v_cvt_pk_bf16_f32 v82, v96, s0
	v_or_b32_e32 v86, 59, v132
	ds_write_b16 v135, v82 offset:8352
	v_cvt_pk_bf16_f32 v82, v97, s0
	v_mad_u32_u24 v86, v86, s0, v137
	v_cvt_pk_bf16_f32 v66, v66, s0
	ds_write_b16 v86, v82
	ds_write_b16 v135, v66 offset:4672
	v_cvt_pk_bf16_f32 v66, v67, s0
	ds_write_b16 v135, v66 offset:4816
	v_cvt_pk_bf16_f32 v66, v68, s0
	ds_write_b16 v135, v66 offset:4960
	v_cvt_pk_bf16_f32 v66, v69, s0
	ds_write_b16 v83, v66 offset:64
	v_cvt_pk_bf16_f32 v66, v70, s0
	ds_write_b16 v135, v66 offset:5824
	v_cvt_pk_bf16_f32 v66, v71, s0
	ds_write_b16 v135, v66 offset:5968
	v_cvt_pk_bf16_f32 v66, v72, s0
	ds_write_b16 v135, v66 offset:6112
	v_cvt_pk_bf16_f32 v66, v73, s0
	ds_write_b16 v84, v66 offset:64
	v_cvt_pk_bf16_f32 v66, v74, s0
	ds_write_b16 v135, v66 offset:6976
	v_cvt_pk_bf16_f32 v66, v75, s0
	ds_write_b16 v135, v66 offset:7120
	v_cvt_pk_bf16_f32 v66, v76, s0
	ds_write_b16 v135, v66 offset:7264
	v_cvt_pk_bf16_f32 v66, v77, s0
	ds_write_b16 v85, v66 offset:64
	v_cvt_pk_bf16_f32 v66, v78, s0
	ds_write_b16 v135, v66 offset:8128
	v_cvt_pk_bf16_f32 v66, v79, s0
	v_or_b32_e32 v133, v133, v134
	ds_write_b16 v135, v66 offset:8272
	v_cvt_pk_bf16_f32 v66, v80, s0
	v_mad_u32_u24 v134, v132, s0, v133
	ds_write_b16 v135, v66 offset:8416
	v_cvt_pk_bf16_f32 v66, v81, s0
	ds_write_b16 v86, v66 offset:64
	s_waitcnt lgkmcnt(0)
	s_barrier
	ds_read_b128 v[66:69], v134
	v_or_b32_e32 v70, v1, v132
	v_mul_i32_i24_e32 v70, 0x14000, v70
	v_ashrrev_i32_e32 v71, 31, v70
	v_or_b32_e32 v72, 8, v132
	v_lshl_add_u64 v[70:71], v[130:131], 0, v[70:71]
	v_mad_u32_u24 v73, v72, s0, v133
	s_waitcnt lgkmcnt(0)
	global_store_dwordx4 v[70:71], v[66:69], off nt
	ds_read_b128 v[66:69], v73
	v_or_b32_e32 v70, v1, v72
	v_mul_i32_i24_e32 v70, 0x14000, v70
	v_ashrrev_i32_e32 v71, 31, v70
	v_lshl_add_u64 v[70:71], v[130:131], 0, v[70:71]
	s_waitcnt lgkmcnt(0)
	global_store_dwordx4 v[70:71], v[66:69], off nt
	v_or_b32_e32 v74, 16, v132
	ds_read_b128 v[66:69], v73 offset:1152
	v_or_b32_e32 v70, v1, v74
	v_mul_i32_i24_e32 v70, 0x14000, v70
	v_ashrrev_i32_e32 v71, 31, v70
	v_lshl_add_u64 v[70:71], v[130:131], 0, v[70:71]
	s_waitcnt lgkmcnt(0)
	global_store_dwordx4 v[70:71], v[66:69], off nt
	v_or_b32_e32 v75, 24, v132
	ds_read_b128 v[66:69], v73 offset:2304
	v_or_b32_e32 v70, v1, v75
	v_mul_i32_i24_e32 v70, 0x14000, v70
	v_ashrrev_i32_e32 v71, 31, v70
	v_lshl_add_u64 v[70:71], v[130:131], 0, v[70:71]
	s_waitcnt lgkmcnt(0)
	global_store_dwordx4 v[70:71], v[66:69], off nt
	v_or_b32_e32 v76, 32, v132
	ds_read_b128 v[66:69], v73 offset:3456
	v_or_b32_e32 v70, v1, v76
	v_mul_i32_i24_e32 v70, 0x14000, v70
	v_ashrrev_i32_e32 v71, 31, v70
	v_lshl_add_u64 v[70:71], v[130:131], 0, v[70:71]
	s_waitcnt lgkmcnt(0)
	global_store_dwordx4 v[70:71], v[66:69], off nt
	v_or_b32_e32 v77, 40, v132
	ds_read_b128 v[66:69], v73 offset:4608
	v_or_b32_e32 v70, v1, v77
	v_mul_i32_i24_e32 v70, 0x14000, v70
	v_ashrrev_i32_e32 v71, 31, v70
	v_lshl_add_u64 v[70:71], v[130:131], 0, v[70:71]
	s_waitcnt lgkmcnt(0)
	global_store_dwordx4 v[70:71], v[66:69], off nt
	v_or_b32_e32 v78, 48, v132
	ds_read_b128 v[66:69], v73 offset:5760
	v_or_b32_e32 v70, v1, v78
	v_mul_i32_i24_e32 v70, 0x14000, v70
	v_ashrrev_i32_e32 v71, 31, v70
	v_lshl_add_u64 v[70:71], v[130:131], 0, v[70:71]
	s_waitcnt lgkmcnt(0)
	global_store_dwordx4 v[70:71], v[66:69], off nt
	v_or_b32_e32 v79, 56, v132
	ds_read_b128 v[66:69], v73 offset:6912
	v_or_b32_e32 v70, v1, v79
	v_mul_i32_i24_e32 v70, 0x14000, v70
	v_ashrrev_i32_e32 v71, 31, v70
	v_lshl_add_u64 v[70:71], v[130:131], 0, v[70:71]
	v_cvt_pk_bf16_f32 v50, v50, s0
	s_waitcnt lgkmcnt(0)
	global_store_dwordx4 v[70:71], v[66:69], off nt
	s_barrier
	ds_write_b16 v135, v50
	v_cvt_pk_bf16_f32 v50, v51, s0
	ds_write_b16 v135, v50 offset:144
	v_cvt_pk_bf16_f32 v50, v52, s0
	ds_write_b16 v135, v50 offset:288
	v_cvt_pk_bf16_f32 v50, v53, s0
	ds_write_b16 v115, v50
	v_cvt_pk_bf16_f32 v50, v54, s0
	ds_write_b16 v135, v50 offset:1152
	v_cvt_pk_bf16_f32 v50, v55, s0
	ds_write_b16 v135, v50 offset:1296
	v_cvt_pk_bf16_f32 v50, v56, s0
	ds_write_b16 v135, v50 offset:1440
	v_cvt_pk_bf16_f32 v50, v57, s0
	ds_write_b16 v116, v50
	v_cvt_pk_bf16_f32 v50, v58, s0
	ds_write_b16 v135, v50 offset:2304
	v_cvt_pk_bf16_f32 v50, v59, s0
	ds_write_b16 v135, v50 offset:2448
	v_cvt_pk_bf16_f32 v50, v60, s0
	ds_write_b16 v135, v50 offset:2592
	v_cvt_pk_bf16_f32 v50, v61, s0
	ds_write_b16 v117, v50
	v_cvt_pk_bf16_f32 v50, v62, s0
	ds_write_b16 v135, v50 offset:3456
	v_cvt_pk_bf16_f32 v50, v63, s0
	ds_write_b16 v135, v50 offset:3600
	v_cvt_pk_bf16_f32 v50, v64, s0
	ds_write_b16 v135, v50 offset:3744
	v_cvt_pk_bf16_f32 v50, v65, s0
	v_cvt_pk_bf16_f32 v34, v34, s0
	ds_write_b16 v118, v50
	ds_write_b16 v135, v34 offset:64
	v_cvt_pk_bf16_f32 v34, v35, s0
	ds_write_b16 v135, v34 offset:208
	v_cvt_pk_bf16_f32 v34, v36, s0
	ds_write_b16 v135, v34 offset:352
	v_cvt_pk_bf16_f32 v34, v37, s0
	ds_write_b16 v115, v34 offset:64
	v_cvt_pk_bf16_f32 v34, v38, s0
	ds_write_b16 v135, v34 offset:1216
	v_cvt_pk_bf16_f32 v34, v39, s0
	ds_write_b16 v135, v34 offset:1360
	v_cvt_pk_bf16_f32 v34, v40, s0
	ds_write_b16 v135, v34 offset:1504
	v_cvt_pk_bf16_f32 v34, v41, s0
	ds_write_b16 v116, v34 offset:64
	v_cvt_pk_bf16_f32 v34, v42, s0
	ds_write_b16 v135, v34 offset:2368
	v_cvt_pk_bf16_f32 v34, v43, s0
	ds_write_b16 v135, v34 offset:2512
	v_cvt_pk_bf16_f32 v34, v44, s0
	ds_write_b16 v135, v34 offset:2656
	v_cvt_pk_bf16_f32 v34, v45, s0
	ds_write_b16 v117, v34 offset:64
	v_cvt_pk_bf16_f32 v34, v46, s0
	ds_write_b16 v135, v34 offset:3520
	v_cvt_pk_bf16_f32 v34, v47, s0
	ds_write_b16 v135, v34 offset:3664
	v_cvt_pk_bf16_f32 v34, v48, s0
	ds_write_b16 v135, v34 offset:3808
	v_cvt_pk_bf16_f32 v34, v49, s0
	v_cvt_pk_bf16_f32 v18, v18, s0
	ds_write_b16 v118, v34 offset:64
	ds_write_b16 v135, v18 offset:4608
	v_cvt_pk_bf16_f32 v18, v19, s0
	ds_write_b16 v135, v18 offset:4752
	v_cvt_pk_bf16_f32 v18, v20, s0
	ds_write_b16 v135, v18 offset:4896
	v_cvt_pk_bf16_f32 v18, v21, s0
	ds_write_b16 v83, v18
	v_cvt_pk_bf16_f32 v18, v22, s0
	ds_write_b16 v135, v18 offset:5760
	v_cvt_pk_bf16_f32 v18, v23, s0
	ds_write_b16 v135, v18 offset:5904
	v_cvt_pk_bf16_f32 v18, v24, s0
	ds_write_b16 v135, v18 offset:6048
	v_cvt_pk_bf16_f32 v18, v25, s0
	ds_write_b16 v84, v18
	v_cvt_pk_bf16_f32 v18, v26, s0
	ds_write_b16 v135, v18 offset:6912
	v_cvt_pk_bf16_f32 v18, v27, s0
	ds_write_b16 v135, v18 offset:7056
	v_cvt_pk_bf16_f32 v18, v28, s0
	ds_write_b16 v135, v18 offset:7200
	v_cvt_pk_bf16_f32 v18, v29, s0
	ds_write_b16 v85, v18
	v_cvt_pk_bf16_f32 v18, v30, s0
	ds_write_b16 v135, v18 offset:8064
	v_cvt_pk_bf16_f32 v18, v31, s0
	ds_write_b16 v135, v18 offset:8208
	v_cvt_pk_bf16_f32 v18, v32, s0
	ds_write_b16 v135, v18 offset:8352
	v_cvt_pk_bf16_f32 v18, v33, s0
	v_cvt_pk_bf16_f32 v2, v2, s0
	ds_write_b16 v86, v18
	ds_write_b16 v135, v2 offset:4672
	v_cvt_pk_bf16_f32 v2, v3, s0
	ds_write_b16 v135, v2 offset:4816
	v_cvt_pk_bf16_f32 v2, v4, s0
	ds_write_b16 v135, v2 offset:4960
	v_cvt_pk_bf16_f32 v2, v5, s0
	ds_write_b16 v83, v2 offset:64
	v_cvt_pk_bf16_f32 v2, v6, s0
	ds_write_b16 v135, v2 offset:5824
	v_cvt_pk_bf16_f32 v2, v7, s0
	ds_write_b16 v135, v2 offset:5968
	v_cvt_pk_bf16_f32 v2, v8, s0
	ds_write_b16 v135, v2 offset:6112
	v_cvt_pk_bf16_f32 v2, v9, s0
	ds_write_b16 v84, v2 offset:64
	v_cvt_pk_bf16_f32 v2, v10, s0
	ds_write_b16 v135, v2 offset:6976
	v_cvt_pk_bf16_f32 v2, v11, s0
	ds_write_b16 v135, v2 offset:7120
	v_cvt_pk_bf16_f32 v2, v12, s0
	ds_write_b16 v135, v2 offset:7264
	v_cvt_pk_bf16_f32 v2, v13, s0
	ds_write_b16 v85, v2 offset:64
	v_cvt_pk_bf16_f32 v2, v14, s0
	ds_write_b16 v135, v2 offset:8128
	v_cvt_pk_bf16_f32 v2, v15, s0
	ds_write_b16 v135, v2 offset:8272
	v_cvt_pk_bf16_f32 v2, v16, s0
	ds_write_b16 v135, v2 offset:8416
	v_cvt_pk_bf16_f32 v2, v17, s0
	ds_write_b16 v86, v2 offset:64
	s_waitcnt lgkmcnt(0)
	s_barrier
	ds_read_b128 v[2:5], v134
	v_or_b32_e32 v1, 64, v1
	v_or_b32_e32 v6, v1, v132
	v_mad_i64_i32 v[6:7], s[0:1], v6, s97, v[130:131]
	s_waitcnt lgkmcnt(0)
	global_store_dwordx4 v[6:7], v[2:5], off nt
	ds_read_b128 v[2:5], v73
	v_or_b32_e32 v6, v1, v72
	v_mad_i64_i32 v[6:7], s[0:1], v6, s97, v[130:131]
	s_waitcnt lgkmcnt(0)
	global_store_dwordx4 v[6:7], v[2:5], off nt
	ds_read_b128 v[2:5], v73 offset:1152
	v_or_b32_e32 v6, v1, v74
	v_mad_i64_i32 v[6:7], s[0:1], v6, s97, v[130:131]
	s_waitcnt lgkmcnt(0)
	global_store_dwordx4 v[6:7], v[2:5], off nt
	ds_read_b128 v[2:5], v73 offset:2304
	v_or_b32_e32 v6, v1, v75
	v_mad_i64_i32 v[6:7], s[0:1], v6, s97, v[130:131]
	s_waitcnt lgkmcnt(0)
	global_store_dwordx4 v[6:7], v[2:5], off nt
	ds_read_b128 v[2:5], v73 offset:3456
	v_or_b32_e32 v6, v1, v76
	v_mad_i64_i32 v[6:7], s[0:1], v6, s97, v[130:131]
	s_waitcnt lgkmcnt(0)
	global_store_dwordx4 v[6:7], v[2:5], off nt
	ds_read_b128 v[2:5], v73 offset:4608
	v_or_b32_e32 v6, v1, v77
	v_mad_i64_i32 v[6:7], s[0:1], v6, s97, v[130:131]
	s_waitcnt lgkmcnt(0)
	global_store_dwordx4 v[6:7], v[2:5], off nt
	ds_read_b128 v[2:5], v73 offset:5760
	v_or_b32_e32 v6, v1, v78
	v_mad_i64_i32 v[6:7], s[0:1], v6, s97, v[130:131]
	v_or_b32_e32 v1, v1, v79
	s_waitcnt lgkmcnt(0)
	global_store_dwordx4 v[6:7], v[2:5], off nt
	ds_read_b128 v[2:5], v73 offset:6912
	v_mad_i64_i32 v[6:7], s[0:1], v1, s97, v[130:131]
	v_readlane_b32 s0, v246, 1
	s_add_i32 s2, s2, s0
	s_cmpk_gt_i32 s2, 0x27f
	s_waitcnt lgkmcnt(0)
	global_store_dwordx4 v[6:7], v[2:5], off nt
	s_barrier
	s_cbranch_scc0 .LBB0_579
